# v7 plus guard: Fourier-GEMM workgroup shift only when grid is 256 workgroups
# speedup vs baseline: 1.0039x; 1.0039x over previous
; #define PG8_STAGE(bufoff, gbase, voff) do { _Pragma("unroll") for (int _i = 0; _i < 2; ++_i) \
;         __builtin_amdgcn_global_load_lds((const unsigned*)((const char*)(gbase) + (voff)[_i]), (LAS unsigned*)(lds + (bufoff) + ldsw + _i * 8192), 16, 0, 0); } while (0)
; #define PG8_WAIT_V(n) asm volatile("s_waitcnt vmcnt(" #n ")" ::: "memory")
; template <class Epi>
; __device__ __forceinline__ void gemm_phase(LAS unsigned char* lds, const Sched& S, const int K, const Epi& E) {
;     ...
;     const int wid = __builtin_amdgcn_readfirstlane(tid >> 6), lane = tid & 63, wr = wid >> 2, wc = wid & 3, fr = lane & 15, fq = lane >> 4;
;     const int nt = K / BK;
;     unsigned voffA[2], voffB[2];
; #pragma unroll
;     for (int i = 0; i < 2; ++i) { int R, C; stage_rc(tid * 16 + i * 8192, R, C); const int Rb = Epi::PERM ? ((R & ~31) + perm32(R & 31)) : R;
;         const int RbT = Epi::BMAP ? ((Rb >> 4) + 256 * (Rb & 15)) : Rb;
;         voffA[i] = (unsigned)(R * S.lda + C) * 2u; voffB[i] = (unsigned)(RbT * S.ldb + C) * 2u; }
;     const size_t kstep = (size_t)(BK * 2);
;     const size_t hstepA = (size_t)HALF * S.lda * 2, hstepB = (size_t)(Epi::BMAP ? 8 : HALF) * S.ldb * 2;
;     const unsigned ldsw = (unsigned)wid * 1024u;
;     const int aoff = lds_byte(wr * 64 + fr, fq * 8), boff = lds_byte(wc * 32 + fr, fq * 8);
;     ...
;     Unit cur, nxt; int ui = 0;
;     if (!S.next(0, cur)) return;
;     f32x4 acc[2][2][4][2];
; #pragma unroll
;     for (int a = 0; a < 2; ++a)
; #pragma unroll
;         for (int b = 0; b < 2; ++b)
; #pragma unroll
;             for (int m = 0; m < 4; ++m)
; #pragma unroll
;                 for (int n = 0; n < 2; ++n) acc[a][b][m][n] = (f32x4){0.f, 0.f, 0.f, 0.f};
;     bf16x8 At[4][2], B0[2][2], B1[2][2];
;     const char* cA = cur.A; const char* cB = cur.B;
;     PG8_STAGE(PG8_SB(0, 0), cB, voffB); PG8_STAGE(PG8_SB(0, 1), cB + hstepB, voffB); PG8_STAGE(PG8_SA(0, 0), cA, voffA); PG8_STAGE(PG8_SA(0, 1), cA + hstepA, voffA);
;     if (wr == 1) PG8_BAR;
;     PG8_WAIT_V(2); PG8_BAR;
;     PG8_STAGE(PG8_SB(1, 0), cB + kstep, voffB); PG8_STAGE(PG8_SA(1, 0), cA + kstep, voffA); PG8_STAGE(PG8_SB(1, 1), cB + hstepB + kstep, voffB);
; __global__ void __launch_bounds__(NTHREADS, 2) mega_fwd(Args a) {
;     ...
;             { pg8::Sched S{(const char*)D256, (const char*)VT, 0, 0, 512, 512, 1, 192, 1, G, bx, 0, 8}; EpiFour2 E{SLOT1}; pg8::gemm_phase(lds, S, 512, E); }
.LBB0_737:
	s_andn2_b64 vcc, exec, s[28:29]
	s_cbranch_vccnz .LBB0_822
	v_readlane_b32 s34, v253, 36
	s_mov_b64 s[38:39], s[22:23]
	s_mov_b32 s0, s68
	s_nop 2
	s_cmpk_lg_i32 s34, 0x100
	s_cbranch_scc1 .Lde_keep
	s_sub_i32 s0, s68, 64
.Lde_keep:
	s_mov_b64 s[28:29], s[20:21]
	s_mov_b32 s2, s34
	s_waitcnt vmcnt(0)
	v_mov_b32_e32 v4, v175
	s_cmpk_gt_u32 s0, 0xbf
	v_readfirstlane_b32 s40, v4
	v_readlane_b32 s35, v253, 37
	s_cbranch_scc1 .LBB0_754
	v_lshlrev_b32_e32 v0, 4, v4
	v_add_u32_e32 v1, 0x2000, v0
	v_ashrrev_i32_e32 v2, 31, v1
	v_lshrrev_b32_e32 v2, 22, v2
	v_add_u32_e32 v2, v1, v2
	v_ashrrev_i32_e32 v5, 10, v2
	v_mul_i32_i24_e32 v2, 0x400, v5
	v_sub_u32_e32 v1, v1, v2
	v_lshrrev_b32_e32 v2, 4, v1
	v_bitop3_b32 v1, v2, v1, 32 bitop3:0x6c
	v_ashrrev_i32_e32 v2, 31, v1
	v_lshrrev_b32_e32 v2, 26, v2
	v_add_u32_e32 v2, v1, v2
	v_lshlrev_b32_e32 v3, 3, v5
	v_ashrrev_i32_e32 v6, 6, v2
	v_and_b32_e32 v3, -16, v3
	v_add_u32_e32 v3, v6, v3
	v_and_b32_e32 v7, 3, v6
	s_mov_b32 s4, 0x3fffe0
	v_lshrrev_b32_e32 v8, 2, v3
	v_lshlrev_b32_e32 v9, 1, v3
	v_and_b32_e32 v2, 0xc0, v2
	v_and_or_b32 v7, v3, s4, v7
	v_and_b32_e32 v8, 4, v8
	v_and_b32_e32 v9, 24, v9
	v_sub_u32_e32 v1, v1, v2
	v_or3_b32 v8, v7, v8, v9
	v_lshlrev_b32_e32 v7, 5, v5
	v_ashrrev_i16_sdwa v1, v249, sext(v1) dst_sel:DWORD dst_unused:UNUSED_PAD src0_sel:DWORD src1_sel:BYTE_0
	v_and_b32_e32 v9, 32, v7
	v_bfe_i32 v7, v1, 0, 16
	v_add_lshl_u32 v1, v9, v7, 1
	v_lshl_add_u32 v128, v8, 10, v1
	v_lshl_add_u32 v130, v3, 10, v1
	v_bfe_i32 v1, v4, 27, 1
	v_lshrrev_b32_e32 v1, 22, v1
	v_add_u32_e32 v1, v0, v1
	v_and_b32_e32 v1, 0xfffffc00, v1
	v_sub_u32_e32 v0, v0, v1
	v_lshrrev_b32_e32 v1, 4, v0
	v_ashrrev_i32_e32 v2, 31, v4
	v_bitop3_b32 v0, v1, v0, 32 bitop3:0x6c
	v_lshrrev_b32_e32 v2, 26, v2
	v_ashrrev_i32_e32 v1, 31, v0
	v_add_u32_e32 v2, v4, v2
	s_add_u32 s34, s38, 0x8850000
	v_lshrrev_b32_e32 v1, 26, v1
	v_ashrrev_i32_e32 v9, 6, v2
	s_addc_u32 s35, s39, 0
	v_add_u32_e32 v1, v0, v1
	v_lshlrev_b32_e32 v2, 3, v9
	s_add_u32 s31, s38, 0x5850000
	v_ashrrev_i32_e32 v8, 6, v1
	v_and_b32_e32 v2, -16, v2
	s_addc_u32 s33, s39, 0
	v_add_u32_e32 v2, v8, v2
	s_and_b32 s29, s0, 7
	v_and_b32_e32 v3, 3, v8
	v_lshrrev_b32_e32 v10, 2, v2
	v_lshlrev_b32_e32 v11, 1, v2
	v_and_b32_e32 v1, 0xc0, v1
	s_lshr_b32 s28, s0, 3
	s_mul_i32 s29, s29, 24
	s_ashr_i32 s41, s40, 6
	v_and_or_b32 v3, v2, s4, v3
	v_and_b32_e32 v10, 4, v10
	v_and_b32_e32 v11, 24, v11
	v_sub_u32_e32 v0, v0, v1
	s_add_i32 s64, s29, s28
	s_ashr_i32 s42, s40, 8
	s_lshl_b32 s54, s41, 10
	v_or3_b32 v3, v3, v10, v11
	v_lshlrev_b32_e32 v10, 5, v9
	v_ashrrev_i16_sdwa v0, v249, sext(v0) dst_sel:DWORD dst_unused:UNUSED_PAD src0_sel:DWORD src1_sel:BYTE_0
	s_lshl_b32 s28, s64, 18
	v_and_b32_e32 v11, 32, v10
	v_bfe_i32 v10, v0, 0, 16
	s_add_u32 s48, s31, s28
	v_add_lshl_u32 v0, v11, v10, 1
	s_addc_u32 s49, s33, 0
	s_add_i32 s55, s54, 0
	v_lshl_add_u32 v132, v3, 10, v0
	s_add_i32 m0, s55, 0x10000
	v_lshl_add_u32 v134, v2, 10, v0
	global_load_lds_dwordx4 v132, s[48:49]
	s_add_i32 m0, s55, 0x12000
	s_add_u32 s28, s48, 0x20000
	global_load_lds_dwordx4 v128, s[48:49]
	s_addc_u32 s29, s49, 0
	s_add_i32 m0, s55, 0x14000
	s_add_i32 s57, s55, 0x2000
	global_load_lds_dwordx4 v132, s[28:29]
	s_add_i32 m0, s55, 0x16000
	v_mov_b32_e32 v133, v173
	global_load_lds_dwordx4 v128, s[28:29]
	s_mov_b32 m0, s55
	s_add_u32 s28, s38, 0x8870000
	global_load_lds_dwordx4 v134, s[34:35]
	s_mov_b32 m0, s57
	s_addc_u32 s29, s39, 0
	s_add_i32 s58, s55, 0x4000
	global_load_lds_dwordx4 v130, s[34:35]
	s_mov_b32 m0, s58
	s_add_i32 s59, s55, 0x6000
	global_load_lds_dwordx4 v134, s[28:29]
	s_mov_b32 m0, s59
	v_mov_b32_e32 v129, v173
	global_load_lds_dwordx4 v130, s[28:29]
	s_cmp_eq_u32 s42, 1
	v_lshl_add_u64 v[0:1], s[48:49], 0, v[132:133]
	s_cselect_b64 s[28:29], -1, 0
	s_cmp_lg_u32 s42, 1
	v_lshl_add_u64 v[2:3], s[48:49], 0, v[128:129]
	s_cbranch_scc1 .LBB0_741
	s_barrier
